# speedup vs baseline: 1.0057x; 1.0057x over previous
; __device__ __forceinline__ void partialSM8(f32x16& p0, f32x16& p1, float& m_reg, float& mn, float& alpha) {
;     ...
;   if (__builtin_expect(__all(pmax - m_reg <= THR8 * 8.f * 1.4426950408889634f), 1)) { mn = m_reg; alpha = 1.f; }
;   else { mn = fmaxf(m_reg, pmax); alpha = __builtin_amdgcn_exp2f((m_reg - mn) * 0.125f); m_reg = mn; }
;   const float mn8 = (P8SHIFT + 7.f - 0.0436f) * 8.f + 0.5f - mn;
; #pragma unroll
;   for (int r = 0; r < 16; ++r) p0[r] += mn8;
; #pragma unroll
;   for (int r = 0; r < 16; ++r) p1[r] += mn8;
.LBB0_928:
	v_cndmask_b32_e64 v216, v169, v168, s[10:11]
	s_add_i32 s18, s18, 2
	s_add_i32 s2, s16, 1
	v_sub_f32_e32 v168, 0x42c04d6a, v216
	s_cmp_lg_u32 s16, 4
	v_add_f32_e32 v184, v96, v168
	v_add_f32_e32 v185, v97, v168
	v_add_f32_e32 v182, v98, v168
	v_add_f32_e32 v183, v99, v168
	v_add_f32_e32 v178, v100, v168
	v_add_f32_e32 v179, v101, v168
	v_add_f32_e32 v174, v102, v168
	v_add_f32_e32 v175, v103, v168
	v_add_f32_e32 v172, v104, v168
	v_add_f32_e32 v173, v105, v168
	v_add_f32_e32 v118, v106, v168
	v_add_f32_e32 v119, v107, v168
	v_add_f32_e32 v116, v108, v168
	v_add_f32_e32 v117, v109, v168
	v_add_f32_e32 v114, v110, v168
	v_add_f32_e32 v115, v111, v168
	v_add_f32_e32 v198, v80, v168
	v_add_f32_e32 v199, v81, v168
	v_add_f32_e32 v196, v82, v168
	v_add_f32_e32 v197, v83, v168
	v_add_f32_e32 v194, v84, v168
	v_add_f32_e32 v195, v85, v168
	v_add_f32_e32 v190, v86, v168
	v_add_f32_e32 v191, v87, v168
	v_add_f32_e32 v188, v88, v168
	v_add_f32_e32 v189, v89, v168
	v_add_f32_e32 v186, v90, v168
	v_add_f32_e32 v187, v91, v168
	v_add_f32_e32 v180, v92, v168
	v_add_f32_e32 v181, v93, v168
	v_add_f32_e32 v176, v94, v168
	v_add_f32_e32 v177, v95, v168
	s_cselect_b32 s21, s2, 0
	s_and_b64 vcc, exec, s[12:13]
	s_cbranch_vccnz .LBB0_930
	s_mov_b32 s22, s19
	s_branch .LBB0_906
